# fused GEMM epilogue part 2: the 12 pre-norm/scale/shift vector loads issued in one batch (5 round trips -> 1)
# baseline (speedup 1.0000x reference)
; __device__ __forceinline__ unsigned cvt_pk_bf16(float lo, float hi) { unsigned r; asm volatile("v_cvt_pk_bf16_f32 %0, %1, %2" : "=v"(r) : "v"(lo), "v"(hi)); return r; }
;     __device__ __forceinline__ void fused(f32x4 (&acc)[2][2][4][2], const Unit& u, int wr, int wc, int fr, int fq, LAS unsigned char* lds, int wid, int lane) const {
;     ...
;         {
;             f32x4 gm[2][2], sh[2][2];
; #pragma unroll
;             for (int bj = 0; bj < 2; ++bj)
; #pragma unroll
;                 for (int n = 0; n < 2; ++n) { const int c = col0 + bj * HALF + n * 16; gm[bj][n] = *(const f32x4*)(gpre + c) * (*(const f32x4*)(scale + mb + c) + 1.0f); sh[bj][n] = *(const f32x4*)(shift + mb + c); }
; #pragma unroll
;             for (int ai = 0; ai < 2; ++ai)
; #pragma unroll
;                 for (int m = 0; m < 4; ++m) { const int r = ai * HALF + wr * 64 + m * 16 + fr; const float r2 = rsqrtf(S[r] * (1.0f / D) + EPS); const size_t off = (size_t)(u.pm * BM + r) * D + col0;
; #pragma unroll
;                     for (int bj = 0; bj < 2; ++bj)
; #pragma unroll
;                         for (int n = 0; n < 2; ++n) { const f32x4 hv = (acc[ai][bj][m][n] * r2) * gm[bj][n] + sh[bj][n];
;                             uint2 w2; w2.x = cvt_pk_bf16(hv[0], hv[1]); w2.y = cvt_pk_bf16(hv[2], hv[3]); *(uint2*)(H + off + bj * HALF + n * 16) = w2; }
.LBB0_1152:
	s_or_b64 exec, exec, s[6:7]
	v_readlane_b32 s6, v253, 51
	s_add_i32 s80, s6, s14
	s_lshl_b64 s[0:1], s[80:81], 12
	s_add_u32 s4, s36, s0
	s_addc_u32 s5, s37, s1
	s_add_i32 s80, s6, s16
	s_lshl_b64 s[0:1], s[80:81], 12
	s_add_u32 s0, s34, s0
	s_addc_u32 s1, s35, s1
	s_add_u32 s0, s0, s94
	v_readlane_b32 s6, v253, 45
	s_addc_u32 s1, s1, s95
	v_readlane_b32 s7, v253, 46
	v_lshl_add_u64 v[134:135], s[0:1], 0, v[128:129]
	s_mov_b32 s0, 0xa300000
	v_lshl_add_u64 v[184:185], s[6:7], 0, v[128:129]
	s_mov_b64 s[6:7], 0xa300000
	v_lshl_add_u64 v[186:187], v[134:135], 0, s[6:7]
	v_add_co_u32_e32 v134, vcc, s0, v134
	s_waitcnt vmcnt(0) lgkmcnt(0)
	s_barrier
	s_nop 0
	v_addc_co_u32_e32 v135, vcc, 0, v135, vcc
	s_add_u32 s4, s4, s94
	s_addc_u32 s5, s5, s95
	v_lshl_add_u64 v[128:129], s[4:5], 0, v[128:129]
	v_lshl_add_u64 v[192:193], v[128:129], 0, s[6:7]
	v_add_co_u32_e32 v128, vcc, s0, v128
	v_lshlrev_b64 v[158:159], 11, v[158:159]
	s_nop 0
	v_addc_co_u32_e32 v129, vcc, 0, v129, vcc
	global_load_dwordx4 v[212:215], v[134:135], off
	global_load_dwordx4 v[228:231], v[184:185], off
	global_load_dwordx4 v[216:219], v[186:187], off offset:64
	global_load_dwordx4 v[232:235], v[184:185], off offset:64
	global_load_dwordx4 v[220:223], v[186:187], off offset:512
	global_load_dwordx4 v[236:239], v[184:185], off offset:512
	global_load_dwordx4 v[224:227], v[186:187], off offset:576
	global_load_dwordx4 v[240:243], v[184:185], off offset:576
	global_load_dwordx4 v[128:131], v[128:129], off
	global_load_dwordx4 v[132:135], v[192:193], off offset:64
	global_load_dwordx4 v[136:139], v[192:193], off offset:512
	global_load_dwordx4 v[140:143], v[192:193], off offset:576
	ds_read_b32 v144, v208 offset:4096
	s_waitcnt vmcnt(4)
	v_pk_add_f32 v[214:215], v[214:215], 1.0 op_sel_hi:[1,0]
	v_pk_add_f32 v[212:213], v[212:213], 1.0 op_sel_hi:[1,0]
	v_pk_mul_f32 v[172:173], v[230:231], v[214:215]
	v_pk_mul_f32 v[174:175], v[228:229], v[212:213]
	v_pk_add_f32 v[218:219], v[218:219], 1.0 op_sel_hi:[1,0]
	v_pk_add_f32 v[216:217], v[216:217], 1.0 op_sel_hi:[1,0]
	v_pk_mul_f32 v[176:177], v[234:235], v[218:219]
	v_pk_mul_f32 v[178:179], v[232:233], v[216:217]
	v_pk_add_f32 v[222:223], v[222:223], 1.0 op_sel_hi:[1,0]
	v_pk_add_f32 v[220:221], v[220:221], 1.0 op_sel_hi:[1,0]
	v_pk_mul_f32 v[180:181], v[238:239], v[222:223]
	v_pk_mul_f32 v[182:183], v[236:237], v[220:221]
	v_pk_add_f32 v[226:227], v[226:227], 1.0 op_sel_hi:[1,0]
	v_pk_add_f32 v[224:225], v[224:225], 1.0 op_sel_hi:[1,0]
	v_pk_mul_f32 v[184:185], v[242:243], v[226:227]
	v_pk_mul_f32 v[186:187], v[240:241], v[224:225]
	s_waitcnt lgkmcnt(0)
	v_fmamk_f32 v144, v144, 0x3a800000, v146
	v_cmp_gt_f32_e32 vcc, s67, v144
	s_nop 0
	s_waitcnt vmcnt(0)
	v_mul_f32_e32 v192, 0x4b800000, v144
	v_cndmask_b32_e32 v144, v144, v192, vcc
	v_rsq_f32_e32 v144, v144
	s_nop 0
	v_mul_f32_e32 v192, 0x45800000, v144
	v_cndmask_b32_e32 v144, v144, v192, vcc
	v_pk_mul_f32 v[88:89], v[88:89], v[144:145] op_sel_hi:[1,0]
	v_pk_mul_f32 v[90:91], v[90:91], v[144:145] op_sel_hi:[1,0]
	v_pk_fma_f32 v[88:89], v[174:175], v[88:89], v[128:129]
	v_pk_fma_f32 v[90:91], v[172:173], v[90:91], v[130:131]
	v_cvt_pk_bf16_f32 v192, v88, v89
	v_lshlrev_b64 v[88:89], 1, v[154:155]
	v_cvt_pk_bf16_f32 v193, v90, v91
	v_lshl_add_u64 v[90:91], s[30:31], 0, v[158:159]
	v_pk_mul_f32 v[104:105], v[104:105], v[144:145] op_sel_hi:[1,0]
	v_pk_mul_f32 v[100:101], v[100:101], v[144:145] op_sel_hi:[1,0]
	v_pk_mul_f32 v[84:85], v[84:85], v[144:145] op_sel_hi:[1,0]
	v_lshl_add_u64 v[90:91], v[90:91], 0, v[88:89]
	v_pk_mul_f32 v[106:107], v[106:107], v[144:145] op_sel_hi:[1,0]
	v_pk_fma_f32 v[104:105], v[178:179], v[104:105], v[132:133]
	v_pk_mul_f32 v[102:103], v[102:103], v[144:145] op_sel_hi:[1,0]
	v_pk_fma_f32 v[100:101], v[182:183], v[100:101], v[136:137]
	v_pk_mul_f32 v[86:87], v[86:87], v[144:145] op_sel_hi:[1,0]
	global_store_dwordx2 v[90:91], v[192:193], off
	v_pk_fma_f32 v[106:107], v[176:177], v[106:107], v[134:135]
	v_cvt_pk_bf16_f32 v104, v104, v105
	v_pk_fma_f32 v[102:103], v[180:181], v[102:103], v[138:139]
	v_cvt_pk_bf16_f32 v105, v106, v107
	global_store_dwordx2 v[90:91], v[104:105], off offset:32
	v_cvt_pk_bf16_f32 v100, v100, v101
	v_cvt_pk_bf16_f32 v101, v102, v103
	global_store_dwordx2 v[90:91], v[100:101], off offset:256
	s_waitcnt lgkmcnt(0)
	s_waitcnt vmcnt(3)
	v_pk_fma_f32 v[84:85], v[186:187], v[84:85], v[140:141]
	v_pk_fma_f32 v[86:87], v[184:185], v[86:87], v[142:143]
	v_cvt_pk_bf16_f32 v84, v84, v85
	s_nop 0
	v_cvt_pk_bf16_f32 v85, v86, v87
	global_store_dwordx2 v[90:91], v[84:85], off offset:288
	ds_read_b32 v84, v208 offset:4160
	v_lshlrev_b64 v[86:87], 11, v[156:157]
	s_waitcnt lgkmcnt(0)
; __device__ __forceinline__ unsigned cvt_pk_bf16(float lo, float hi) { unsigned r; asm volatile("v_cvt_pk_bf16_f32 %0, %1, %2" : "=v"(r) : "v"(lo), "v"(hi)); return r; }
;     __device__ __forceinline__ void fused(f32x4 (&acc)[2][2][4][2], const Unit& u, int wr, int wc, int fr, int fq, LAS unsigned char* lds, int wid, int lane) const {
;     ...
;             for (int ai = 0; ai < 2; ++ai)
; #pragma unroll
;                 for (int m = 0; m < 4; ++m) { const int r = ai * HALF + wr * 64 + m * 16 + fr; const float r2 = rsqrtf(S[r] * (1.0f / D) + EPS); const size_t off = (size_t)(u.pm * BM + r) * D + col0;
; #pragma unroll
;                     for (int bj = 0; bj < 2; ++bj)
; #pragma unroll
;                         for (int n = 0; n < 2; ++n) { const f32x4 hv = (acc[ai][bj][m][n] * r2) * gm[bj][n] + sh[bj][n];
;                             uint2 w2; w2.x = cvt_pk_bf16(hv[0], hv[1]); w2.y = cvt_pk_bf16(hv[2], hv[3]); *(uint2*)(H + off + bj * HALF + n * 16) = w2; }
;                     asm volatile("" ::: "memory"); }
	v_fmamk_f32 v84, v84, 0x3a800000, v146
	v_cmp_gt_f32_e32 vcc, s67, v84
	v_mul_f32_e32 v85, 0x4b800000, v84
	s_nop 0
	v_cndmask_b32_e32 v84, v84, v85, vcc
	v_rsq_f32_e32 v84, v84
	s_nop 0
	v_mul_f32_e32 v85, 0x45800000, v84
	v_cndmask_b32_e32 v84, v84, v85, vcc
	v_pk_mul_f32 v[76:77], v[76:77], v[84:85] op_sel_hi:[1,0]
	v_pk_mul_f32 v[78:79], v[78:79], v[84:85] op_sel_hi:[1,0]
	v_pk_fma_f32 v[76:77], v[174:175], v[76:77], v[128:129]
	v_pk_fma_f32 v[78:79], v[172:173], v[78:79], v[130:131]
	v_cvt_pk_bf16_f32 v76, v76, v77
	v_pk_mul_f32 v[72:73], v[72:73], v[84:85] op_sel_hi:[1,0]
	v_cvt_pk_bf16_f32 v77, v78, v79
	v_lshl_add_u64 v[78:79], s[30:31], 0, v[86:87]
	v_lshl_add_u64 v[78:79], v[78:79], 0, v[88:89]
	global_store_dwordx2 v[78:79], v[76:77], off
	v_pk_mul_f32 v[76:77], v[92:93], v[84:85] op_sel_hi:[1,0]
	v_pk_mul_f32 v[86:87], v[94:95], v[84:85] op_sel_hi:[1,0]
	v_pk_fma_f32 v[76:77], v[178:179], v[76:77], v[132:133]
	v_pk_fma_f32 v[86:87], v[176:177], v[86:87], v[134:135]
	v_cvt_pk_bf16_f32 v76, v76, v77
	v_pk_mul_f32 v[74:75], v[74:75], v[84:85] op_sel_hi:[1,0]
	v_cvt_pk_bf16_f32 v77, v86, v87
	global_store_dwordx2 v[78:79], v[76:77], off offset:32
	v_pk_mul_f32 v[76:77], v[80:81], v[84:85] op_sel_hi:[1,0]
	v_pk_mul_f32 v[80:81], v[82:83], v[84:85] op_sel_hi:[1,0]
	v_pk_fma_f32 v[76:77], v[182:183], v[76:77], v[136:137]
	v_pk_fma_f32 v[72:73], v[186:187], v[72:73], v[140:141]
	v_pk_fma_f32 v[80:81], v[180:181], v[80:81], v[138:139]
	v_cvt_pk_bf16_f32 v76, v76, v77
	v_pk_fma_f32 v[74:75], v[184:185], v[74:75], v[142:143]
	v_cvt_pk_bf16_f32 v77, v80, v81
	global_store_dwordx2 v[78:79], v[76:77], off offset:256
	v_cvt_pk_bf16_f32 v72, v72, v73
	v_cvt_pk_bf16_f32 v73, v74, v75
	global_store_dwordx2 v[78:79], v[72:73], off offset:288
	ds_read_b32 v72, v208 offset:4224
	v_lshlrev_b64 v[74:75], 11, v[160:161]
	v_lshl_add_u64 v[74:75], s[30:31], 0, v[74:75]
	v_lshl_add_u64 v[74:75], v[74:75], 0, v[88:89]
	s_waitcnt lgkmcnt(0)
	v_fmamk_f32 v72, v72, 0x3a800000, v146
	v_cmp_gt_f32_e32 vcc, s67, v72
	v_mul_f32_e32 v73, 0x4b800000, v72
	s_nop 0
	v_cndmask_b32_e32 v72, v72, v73, vcc
	v_rsq_f32_e32 v72, v72
	s_nop 0
	v_mul_f32_e32 v73, 0x45800000, v72
	v_cndmask_b32_e32 v72, v72, v73, vcc
	v_pk_mul_f32 v[76:77], v[108:109], v[72:73] op_sel_hi:[1,0]
	v_pk_mul_f32 v[78:79], v[110:111], v[72:73] op_sel_hi:[1,0]
	v_pk_fma_f32 v[76:77], v[174:175], v[76:77], v[128:129]
	v_pk_fma_f32 v[78:79], v[172:173], v[78:79], v[130:131]
	v_cvt_pk_bf16_f32 v76, v76, v77
	s_nop 0
	v_cvt_pk_bf16_f32 v77, v78, v79
	global_store_dwordx2 v[74:75], v[76:77], off
	v_pk_mul_f32 v[76:77], v[124:125], v[72:73] op_sel_hi:[1,0]
	v_pk_mul_f32 v[78:79], v[126:127], v[72:73] op_sel_hi:[1,0]
	v_pk_fma_f32 v[76:77], v[178:179], v[76:77], v[132:133]
	v_pk_fma_f32 v[78:79], v[176:177], v[78:79], v[134:135]
	v_cvt_pk_bf16_f32 v76, v76, v77
	s_nop 0
	v_cvt_pk_bf16_f32 v77, v78, v79
	global_store_dwordx2 v[74:75], v[76:77], off offset:32
	v_pk_mul_f32 v[76:77], v[120:121], v[72:73] op_sel_hi:[1,0]
	v_pk_mul_f32 v[78:79], v[122:123], v[72:73] op_sel_hi:[1,0]
	v_pk_fma_f32 v[76:77], v[182:183], v[76:77], v[136:137]
	v_pk_fma_f32 v[78:79], v[180:181], v[78:79], v[138:139]
	v_cvt_pk_bf16_f32 v76, v76, v77
	s_nop 0
	v_cvt_pk_bf16_f32 v77, v78, v79
	global_store_dwordx2 v[74:75], v[76:77], off offset:256
	v_pk_mul_f32 v[76:77], v[116:117], v[72:73] op_sel_hi:[1,0]
	v_pk_mul_f32 v[72:73], v[118:119], v[72:73] op_sel_hi:[1,0]
	v_pk_fma_f32 v[76:77], v[186:187], v[76:77], v[140:141]
	v_pk_fma_f32 v[72:73], v[184:185], v[72:73], v[142:143]
	v_cvt_pk_bf16_f32 v76, v76, v77
	s_nop 0
	v_cvt_pk_bf16_f32 v77, v72, v73
	global_store_dwordx2 v[74:75], v[76:77], off offset:288
	ds_read_b32 v72, v208 offset:4288
	v_lshlrev_b64 v[74:75], 11, v[162:163]
	v_lshl_add_u64 v[74:75], s[30:31], 0, v[74:75]
	v_lshl_add_u64 v[74:75], v[74:75], 0, v[88:89]
	s_waitcnt lgkmcnt(0)
	v_fmamk_f32 v72, v72, 0x3a800000, v146
	v_cmp_gt_f32_e32 vcc, s67, v72
	v_mul_f32_e32 v73, 0x4b800000, v72
	s_nop 0
	v_cndmask_b32_e32 v72, v72, v73, vcc
	v_rsq_f32_e32 v72, v72
	s_nop 0
	v_mul_f32_e32 v73, 0x45800000, v72
	v_cndmask_b32_e32 v72, v72, v73, vcc
	v_pk_mul_f32 v[76:77], v[112:113], v[72:73] op_sel_hi:[1,0]
	v_pk_mul_f32 v[78:79], v[114:115], v[72:73] op_sel_hi:[1,0]
	v_pk_fma_f32 v[76:77], v[174:175], v[76:77], v[128:129]
	v_pk_fma_f32 v[78:79], v[172:173], v[78:79], v[130:131]
	v_cvt_pk_bf16_f32 v76, v76, v77
	v_pk_mul_f32 v[68:69], v[68:69], v[72:73] op_sel_hi:[1,0]
	v_cvt_pk_bf16_f32 v77, v78, v79
	global_store_dwordx2 v[74:75], v[76:77], off
	v_pk_mul_f32 v[76:77], v[96:97], v[72:73] op_sel_hi:[1,0]
	v_pk_mul_f32 v[64:65], v[64:65], v[72:73] op_sel_hi:[1,0]
	v_pk_mul_f32 v[78:79], v[98:99], v[72:73] op_sel_hi:[1,0]
	v_pk_fma_f32 v[76:77], v[178:179], v[76:77], v[132:133]
	v_pk_mul_f32 v[70:71], v[70:71], v[72:73] op_sel_hi:[1,0]
	v_pk_fma_f32 v[68:69], v[182:183], v[68:69], v[136:137]
	v_pk_mul_f32 v[66:67], v[66:67], v[72:73] op_sel_hi:[1,0]
	v_pk_fma_f32 v[64:65], v[186:187], v[64:65], v[140:141]
	v_pk_fma_f32 v[78:79], v[176:177], v[78:79], v[134:135]
	v_cvt_pk_bf16_f32 v76, v76, v77
	v_pk_fma_f32 v[70:71], v[180:181], v[70:71], v[138:139]
	v_cvt_pk_bf16_f32 v77, v78, v79
	global_store_dwordx2 v[74:75], v[76:77], off offset:32
	v_cvt_pk_bf16_f32 v68, v68, v69
	v_cvt_pk_bf16_f32 v69, v70, v71
	global_store_dwordx2 v[74:75], v[68:69], off offset:256
	v_pk_fma_f32 v[66:67], v[184:185], v[66:67], v[142:143]
	v_cvt_pk_bf16_f32 v64, v64, v65
	s_nop 0
	v_cvt_pk_bf16_f32 v65, v66, v67
	global_store_dwordx2 v[74:75], v[64:65], off offset:288
	ds_read_b32 v64, v208 offset:4608
	v_lshlrev_b64 v[66:67], 11, v[164:165]
	s_waitcnt lgkmcnt(0)
; __device__ __forceinline__ unsigned cvt_pk_bf16(float lo, float hi) { unsigned r; asm volatile("v_cvt_pk_bf16_f32 %0, %1, %2" : "=v"(r) : "v"(lo), "v"(hi)); return r; }
;     __device__ __forceinline__ void fused(f32x4 (&acc)[2][2][4][2], const Unit& u, int wr, int wc, int fr, int fq, LAS unsigned char* lds, int wid, int lane) const {
;     ...
;             for (int ai = 0; ai < 2; ++ai)
; #pragma unroll
;                 for (int m = 0; m < 4; ++m) { const int r = ai * HALF + wr * 64 + m * 16 + fr; const float r2 = rsqrtf(S[r] * (1.0f / D) + EPS); const size_t off = (size_t)(u.pm * BM + r) * D + col0;
; #pragma unroll
;                     for (int bj = 0; bj < 2; ++bj)
; #pragma unroll
;                         for (int n = 0; n < 2; ++n) { const f32x4 hv = (acc[ai][bj][m][n] * r2) * gm[bj][n] + sh[bj][n];
;                             uint2 w2; w2.x = cvt_pk_bf16(hv[0], hv[1]); w2.y = cvt_pk_bf16(hv[2], hv[3]); *(uint2*)(H + off + bj * HALF + n * 16) = w2; }
;                     asm volatile("" ::: "memory"); }
	v_fmamk_f32 v64, v64, 0x3a800000, v146
	v_cmp_gt_f32_e32 vcc, s67, v64
	v_mul_f32_e32 v65, 0x4b800000, v64
	s_nop 0
	v_cndmask_b32_e32 v64, v64, v65, vcc
	v_rsq_f32_e32 v64, v64
	s_nop 0
	v_mul_f32_e32 v65, 0x45800000, v64
	v_cndmask_b32_e32 v64, v64, v65, vcc
	v_pk_mul_f32 v[60:61], v[60:61], v[64:65] op_sel_hi:[1,0]
	v_pk_mul_f32 v[62:63], v[62:63], v[64:65] op_sel_hi:[1,0]
	v_pk_fma_f32 v[60:61], v[174:175], v[60:61], v[128:129]
	v_pk_fma_f32 v[62:63], v[172:173], v[62:63], v[130:131]
	v_cvt_pk_bf16_f32 v60, v60, v61
	v_pk_mul_f32 v[56:57], v[56:57], v[64:65] op_sel_hi:[1,0]
	v_cvt_pk_bf16_f32 v61, v62, v63
	v_lshl_add_u64 v[62:63], s[30:31], 0, v[66:67]
	v_pk_mul_f32 v[52:53], v[52:53], v[64:65] op_sel_hi:[1,0]
	v_pk_mul_f32 v[48:49], v[48:49], v[64:65] op_sel_hi:[1,0]
	v_lshl_add_u64 v[62:63], v[62:63], 0, v[88:89]
	v_pk_mul_f32 v[58:59], v[58:59], v[64:65] op_sel_hi:[1,0]
	v_pk_fma_f32 v[56:57], v[178:179], v[56:57], v[132:133]
	v_pk_mul_f32 v[54:55], v[54:55], v[64:65] op_sel_hi:[1,0]
	v_pk_fma_f32 v[52:53], v[182:183], v[52:53], v[136:137]
	v_pk_mul_f32 v[50:51], v[50:51], v[64:65] op_sel_hi:[1,0]
	v_pk_fma_f32 v[48:49], v[186:187], v[48:49], v[140:141]
	global_store_dwordx2 v[62:63], v[60:61], off
	v_pk_fma_f32 v[58:59], v[176:177], v[58:59], v[134:135]
	v_cvt_pk_bf16_f32 v56, v56, v57
	v_pk_fma_f32 v[54:55], v[180:181], v[54:55], v[138:139]
	v_cvt_pk_bf16_f32 v57, v58, v59
	global_store_dwordx2 v[62:63], v[56:57], off offset:32
	v_cvt_pk_bf16_f32 v52, v52, v53
	v_cvt_pk_bf16_f32 v53, v54, v55
	global_store_dwordx2 v[62:63], v[52:53], off offset:256
	v_pk_fma_f32 v[50:51], v[184:185], v[50:51], v[142:143]
	v_cvt_pk_bf16_f32 v48, v48, v49
	s_nop 0
	v_cvt_pk_bf16_f32 v49, v50, v51
	global_store_dwordx2 v[62:63], v[48:49], off offset:288
	ds_read_b32 v48, v208 offset:4672
	v_lshlrev_b64 v[50:51], 11, v[166:167]
	s_waitcnt lgkmcnt(0)
	v_fmamk_f32 v48, v48, 0x3a800000, v146
	v_cmp_gt_f32_e32 vcc, s67, v48
	v_mul_f32_e32 v49, 0x4b800000, v48
	s_nop 0
	v_cndmask_b32_e32 v48, v48, v49, vcc
	v_rsq_f32_e32 v48, v48
	s_nop 0
	v_mul_f32_e32 v49, 0x45800000, v48
	v_cndmask_b32_e32 v48, v48, v49, vcc
	v_pk_mul_f32 v[44:45], v[44:45], v[48:49] op_sel_hi:[1,0]
	v_pk_mul_f32 v[46:47], v[46:47], v[48:49] op_sel_hi:[1,0]
	v_pk_fma_f32 v[44:45], v[174:175], v[44:45], v[128:129]
	v_pk_fma_f32 v[46:47], v[172:173], v[46:47], v[130:131]
	v_cvt_pk_bf16_f32 v44, v44, v45
	v_pk_mul_f32 v[40:41], v[40:41], v[48:49] op_sel_hi:[1,0]
	v_cvt_pk_bf16_f32 v45, v46, v47
	v_lshl_add_u64 v[46:47], s[30:31], 0, v[50:51]
	v_pk_mul_f32 v[36:37], v[36:37], v[48:49] op_sel_hi:[1,0]
	v_pk_mul_f32 v[32:33], v[32:33], v[48:49] op_sel_hi:[1,0]
	v_lshl_add_u64 v[46:47], v[46:47], 0, v[88:89]
	v_pk_mul_f32 v[42:43], v[42:43], v[48:49] op_sel_hi:[1,0]
	v_pk_fma_f32 v[40:41], v[178:179], v[40:41], v[132:133]
	v_pk_mul_f32 v[38:39], v[38:39], v[48:49] op_sel_hi:[1,0]
	v_pk_fma_f32 v[36:37], v[182:183], v[36:37], v[136:137]
	v_pk_mul_f32 v[34:35], v[34:35], v[48:49] op_sel_hi:[1,0]
	v_pk_fma_f32 v[32:33], v[186:187], v[32:33], v[140:141]
	global_store_dwordx2 v[46:47], v[44:45], off
	v_pk_fma_f32 v[42:43], v[176:177], v[42:43], v[134:135]
	v_cvt_pk_bf16_f32 v40, v40, v41
	v_pk_fma_f32 v[38:39], v[180:181], v[38:39], v[138:139]
	v_cvt_pk_bf16_f32 v41, v42, v43
	global_store_dwordx2 v[46:47], v[40:41], off offset:32
	v_cvt_pk_bf16_f32 v36, v36, v37
	v_cvt_pk_bf16_f32 v37, v38, v39
	global_store_dwordx2 v[46:47], v[36:37], off offset:256
	v_pk_fma_f32 v[34:35], v[184:185], v[34:35], v[142:143]
	v_cvt_pk_bf16_f32 v32, v32, v33
	s_nop 0
	v_cvt_pk_bf16_f32 v33, v34, v35
	global_store_dwordx2 v[46:47], v[32:33], off offset:288
	ds_read_b32 v32, v208 offset:4736
	v_lshlrev_b64 v[34:35], 11, v[168:169]
	s_waitcnt lgkmcnt(0)
; __device__ __forceinline__ unsigned cvt_pk_bf16(float lo, float hi) { unsigned r; asm volatile("v_cvt_pk_bf16_f32 %0, %1, %2" : "=v"(r) : "v"(lo), "v"(hi)); return r; }
;     __device__ __forceinline__ void fused(f32x4 (&acc)[2][2][4][2], const Unit& u, int wr, int wc, int fr, int fq, LAS unsigned char* lds, int wid, int lane) const {
;     ...
;             for (int ai = 0; ai < 2; ++ai)
; #pragma unroll
;                 for (int m = 0; m < 4; ++m) { const int r = ai * HALF + wr * 64 + m * 16 + fr; const float r2 = rsqrtf(S[r] * (1.0f / D) + EPS); const size_t off = (size_t)(u.pm * BM + r) * D + col0;
; #pragma unroll
;                     for (int bj = 0; bj < 2; ++bj)
; #pragma unroll
;                         for (int n = 0; n < 2; ++n) { const f32x4 hv = (acc[ai][bj][m][n] * r2) * gm[bj][n] + sh[bj][n];
;                             uint2 w2; w2.x = cvt_pk_bf16(hv[0], hv[1]); w2.y = cvt_pk_bf16(hv[2], hv[3]); *(uint2*)(H + off + bj * HALF + n * 16) = w2; }
;                     asm volatile("" ::: "memory"); }
	v_fmamk_f32 v32, v32, 0x3a800000, v146
	v_cmp_gt_f32_e32 vcc, s67, v32
	v_mul_f32_e32 v33, 0x4b800000, v32
	s_nop 0
	v_cndmask_b32_e32 v32, v32, v33, vcc
	v_rsq_f32_e32 v32, v32
	s_nop 0
	v_mul_f32_e32 v33, 0x45800000, v32
	v_cndmask_b32_e32 v32, v32, v33, vcc
	v_pk_mul_f32 v[28:29], v[28:29], v[32:33] op_sel_hi:[1,0]
	v_pk_mul_f32 v[30:31], v[30:31], v[32:33] op_sel_hi:[1,0]
	v_pk_fma_f32 v[28:29], v[174:175], v[28:29], v[128:129]
	v_pk_fma_f32 v[30:31], v[172:173], v[30:31], v[130:131]
	v_cvt_pk_bf16_f32 v28, v28, v29
	v_pk_mul_f32 v[24:25], v[24:25], v[32:33] op_sel_hi:[1,0]
	v_cvt_pk_bf16_f32 v29, v30, v31
	v_lshl_add_u64 v[30:31], s[30:31], 0, v[34:35]
	v_pk_mul_f32 v[20:21], v[20:21], v[32:33] op_sel_hi:[1,0]
	v_pk_mul_f32 v[16:17], v[16:17], v[32:33] op_sel_hi:[1,0]
	v_lshl_add_u64 v[30:31], v[30:31], 0, v[88:89]
	v_pk_mul_f32 v[26:27], v[26:27], v[32:33] op_sel_hi:[1,0]
	v_pk_fma_f32 v[24:25], v[178:179], v[24:25], v[132:133]
	v_pk_mul_f32 v[22:23], v[22:23], v[32:33] op_sel_hi:[1,0]
	v_pk_fma_f32 v[20:21], v[182:183], v[20:21], v[136:137]
	v_pk_mul_f32 v[18:19], v[18:19], v[32:33] op_sel_hi:[1,0]
	v_pk_fma_f32 v[16:17], v[186:187], v[16:17], v[140:141]
	global_store_dwordx2 v[30:31], v[28:29], off
	v_pk_fma_f32 v[26:27], v[176:177], v[26:27], v[134:135]
	v_cvt_pk_bf16_f32 v24, v24, v25
	v_pk_fma_f32 v[22:23], v[180:181], v[22:23], v[138:139]
	v_cvt_pk_bf16_f32 v25, v26, v27
	global_store_dwordx2 v[30:31], v[24:25], off offset:32
	v_cvt_pk_bf16_f32 v20, v20, v21
	v_cvt_pk_bf16_f32 v21, v22, v23
	global_store_dwordx2 v[30:31], v[20:21], off offset:256
	v_pk_fma_f32 v[18:19], v[184:185], v[18:19], v[142:143]
	v_cvt_pk_bf16_f32 v16, v16, v17
	s_nop 0
	v_cvt_pk_bf16_f32 v17, v18, v19
	global_store_dwordx2 v[30:31], v[16:17], off offset:288
	ds_read_b32 v16, v208 offset:4800
	v_lshlrev_b64 v[18:19], 11, v[170:171]
	s_waitcnt lgkmcnt(0)
	v_fmamk_f32 v16, v16, 0x3a800000, v146
	v_cmp_gt_f32_e32 vcc, s67, v16
	v_mul_f32_e32 v17, 0x4b800000, v16
	s_nop 0
	v_cndmask_b32_e32 v16, v16, v17, vcc
	v_rsq_f32_e32 v16, v16
	s_nop 0
	v_mul_f32_e32 v17, 0x45800000, v16
	v_cndmask_b32_e32 v16, v16, v17, vcc
	v_pk_mul_f32 v[12:13], v[12:13], v[16:17] op_sel_hi:[1,0]
	v_pk_mul_f32 v[14:15], v[14:15], v[16:17] op_sel_hi:[1,0]
	v_pk_fma_f32 v[12:13], v[174:175], v[12:13], v[128:129]
	v_pk_fma_f32 v[14:15], v[172:173], v[14:15], v[130:131]
	v_cvt_pk_bf16_f32 v12, v12, v13
	v_pk_mul_f32 v[8:9], v[8:9], v[16:17] op_sel_hi:[1,0]
	v_cvt_pk_bf16_f32 v13, v14, v15
	v_lshl_add_u64 v[14:15], s[30:31], 0, v[18:19]
	v_pk_mul_f32 v[4:5], v[4:5], v[16:17] op_sel_hi:[1,0]
	v_pk_mul_f32 v[0:1], v[0:1], v[16:17] op_sel_hi:[1,0]
	v_lshl_add_u64 v[14:15], v[14:15], 0, v[88:89]
	v_pk_mul_f32 v[10:11], v[10:11], v[16:17] op_sel_hi:[1,0]
	v_pk_fma_f32 v[8:9], v[178:179], v[8:9], v[132:133]
	v_pk_mul_f32 v[6:7], v[6:7], v[16:17] op_sel_hi:[1,0]
	v_pk_fma_f32 v[4:5], v[182:183], v[4:5], v[136:137]
	v_pk_mul_f32 v[2:3], v[2:3], v[16:17] op_sel_hi:[1,0]
	v_pk_fma_f32 v[0:1], v[186:187], v[0:1], v[140:141]
	global_store_dwordx2 v[14:15], v[12:13], off
	v_pk_fma_f32 v[10:11], v[176:177], v[10:11], v[134:135]
	v_cvt_pk_bf16_f32 v8, v8, v9
	v_pk_fma_f32 v[6:7], v[180:181], v[6:7], v[138:139]
	v_cvt_pk_bf16_f32 v9, v10, v11
	global_store_dwordx2 v[14:15], v[8:9], off offset:32
	v_cvt_pk_bf16_f32 v4, v4, v5
	v_cvt_pk_bf16_f32 v5, v6, v7
	global_store_dwordx2 v[14:15], v[4:5], off offset:256
	v_pk_fma_f32 v[2:3], v[184:185], v[2:3], v[142:143]
	v_cvt_pk_bf16_f32 v0, v0, v1
	s_nop 0
	v_cvt_pk_bf16_f32 v1, v2, v3
	global_store_dwordx2 v[14:15], v[0:1], off offset:288
	s_waitcnt vmcnt(29)
